# FFO residual epilogue: 16-dword L2 touch burst of the y_old tile in the pointer preamble; on top of barrier trims + no setprio flips
# baseline (speedup 1.0000x reference)
.LBB0_1024:
	s_add_u32 s18, s12, 0x1aa00000
	s_addc_u32 s19, s13, 0
	v_lshl_add_u32 v138, v191, 3, s70
	v_and_b32_e32 v139, 0x100, v0
	v_lshl_add_u32 v138, s3, 8, v138
	v_lshrrev_b32_e32 v139, 2, v139
	v_add_u32_e32 v139, v139, v189
	v_lshl_add_u32 v139, s4, 8, v139
	v_lshlrev_b32_e32 v139, 12, v139
	v_lshl_add_u32 v139, v138, 1, v139
	global_load_dword v141, v139, s[18:19]
	global_load_dword v141, v139, s[18:19] offset:256
	v_add_u32_e32 v140, 0x10000, v139
	global_load_dword v141, v140, s[18:19]
	global_load_dword v141, v140, s[18:19] offset:256
	v_add_u32_e32 v140, 0x20000, v139
	global_load_dword v141, v140, s[18:19]
	global_load_dword v141, v140, s[18:19] offset:256
	v_add_u32_e32 v140, 0x30000, v139
	global_load_dword v141, v140, s[18:19]
	global_load_dword v141, v140, s[18:19] offset:256
	v_add_u32_e32 v140, 0x80000, v139
	global_load_dword v141, v140, s[18:19]
	global_load_dword v141, v140, s[18:19] offset:256
	v_add_u32_e32 v140, 0x90000, v139
	global_load_dword v141, v140, s[18:19]
	global_load_dword v141, v140, s[18:19] offset:256
	v_add_u32_e32 v140, 0xa0000, v139
	global_load_dword v141, v140, s[18:19]
	global_load_dword v141, v140, s[18:19] offset:256
	v_add_u32_e32 v140, 0xb0000, v139
	global_load_dword v141, v140, s[18:19]
	global_load_dword v141, v140, s[18:19] offset:256
	s_mul_hi_i32 s9, s8, 0x12000
	s_mul_i32 s8, s8, 0x12000
	s_add_u32 s8, s12, s8
	s_addc_u32 s9, s13, s9
	s_add_u32 s16, s8, 0x20000
	v_readlane_b32 s8, v254, 38
	s_addc_u32 s17, s9, 0
	s_and_b64 vcc, exec, s[6:7]
	v_mov_b32_e32 v2, s8
	ds_read_b32 v2, v2
	v_readlane_b32 s8, v254, 39
	s_waitcnt lgkmcnt(0)
	s_nop 0
	v_mov_b32_e32 v2, s8
	ds_read_b32 v2, v2
	v_readlane_b32 s8, v254, 40
	s_waitcnt lgkmcnt(0)
	s_nop 0
	v_mov_b32_e32 v2, s8
	ds_read_b32 v2, v2
	v_readlane_b32 s8, v254, 41
	s_waitcnt lgkmcnt(0)
	s_nop 0
	v_mov_b32_e32 v2, s8
	ds_read_b32 v2, v2
	v_readlane_b32 s8, v255, 18
	s_waitcnt lgkmcnt(0)
	v_lshl_add_u32 v2, v191, 3, s70
	v_lshl_add_u32 v178, s3, 8, v2
	v_add_u32_e32 v4, s8, v189
	v_lshl_add_u32 v180, s4, 8, v4
	s_cbranch_vccnz .LBB0_1082
	v_ashrrev_i32_e32 v181, 31, v180
	v_lshlrev_b64 v[206:207], 12, v[180:181]
	s_mov_b64 s[0:1], 0x10000
	v_lshl_add_u64 v[212:213], v[206:207], 0, s[0:1]
	s_mov_b64 s[0:1], 0x20000
	v_ashrrev_i32_e32 v179, 31, v178
	v_lshl_add_u64 v[210:211], v[206:207], 0, s[0:1]
	s_mov_b64 s[0:1], 0x30000
	v_lshl_add_u64 v[182:183], v[178:179], 1, s[18:19]
	v_lshl_add_u64 v[208:209], v[206:207], 0, s[0:1]
	v_lshl_add_u64 v[204:205], v[182:183], 0, v[212:213]
	v_lshl_add_u64 v[184:185], v[182:183], 0, v[208:209]
	v_lshl_add_u64 v[186:187], v[182:183], 0, v[210:211]
	global_load_dwordx4 v[170:173], v[204:205], off
	global_load_dwordx4 v[166:169], v[186:187], off
	global_load_dwordx4 v[158:161], v[184:185], off
	v_lshlrev_b32_e32 v4, 3, v4
	v_add_u32_e32 v214, 0, v4
	v_add_u32_e32 v4, 0x20000, v214
	ds_read2_b64 v[174:177], v4 offset1:16
	v_lshl_add_u32 v2, v2, 2, 0
	v_add_u32_e32 v197, 0x20800, v2
	v_add_u32_e32 v199, 0x20c00, v2
	ds_read2_b64 v[162:165], v4 offset0:32 offset1:48
	s_waitcnt lgkmcnt(0)
	v_mul_f32_e32 v201, 0x3a000000, v174
	v_mul_f32_e32 v5, v201, v201
	v_fma_f32 v5, v175, s72, -v5
	v_add_f32_e32 v5, 0x3727c5ac, v5
	s_waitcnt vmcnt(0)
	ds_read_b128 v[150:153], v197
	ds_read_b128 v[142:145], v197 offset:16
	ds_read_b128 v[154:157], v199
	ds_read_b128 v[146:149], v199 offset:16
	v_rsq_f32_e32 v174, v5
	s_and_b32 s6, s84, 1
	s_bitcmp1_b32 s84, 0
	s_cselect_b64 s[0:1], -1, 0
	s_cmp_eq_u32 s6, 0
	s_cbranch_scc1 .LBB0_1048
	v_lshl_add_u64 v[4:5], v[182:183], 0, v[206:207]
	global_load_dwordx4 v[134:137], v[4:5], off
	s_waitcnt vmcnt(0)
	v_lshlrev_b32_e32 v2, 16, v134
	v_and_b32_e32 v4, 0xffff0000, v134
	v_lshlrev_b32_e32 v134, 16, v135
	v_and_b32_e32 v135, 0xffff0000, v135
	v_lshlrev_b32_e32 v175, 16, v136
	v_sub_f32_e32 v5, v4, v201
	v_sub_f32_e32 v4, v2, v201
	v_sub_f32_e32 v135, v135, v201
	v_sub_f32_e32 v134, v134, v201
	v_pk_mul_f32 v[134:135], v[174:175], v[134:135] op_sel_hi:[0,1]
	v_pk_mul_f32 v[4:5], v[174:175], v[4:5] op_sel_hi:[0,1]
	s_waitcnt lgkmcnt(1)
	v_pk_fma_f32 v[4:5], v[150:151], v[4:5], v[154:155]
	v_pk_fma_f32 v[134:135], v[152:153], v[134:135], v[156:157]
	v_and_b32_e32 v136, 0xffff0000, v136
	v_lshlrev_b32_e32 v203, 16, v137
	v_and_b32_e32 v137, 0xffff0000, v137
	v_pk_mul_f32 v[134:135], v[134:135], s[76:77] op_sel_hi:[1,0]
	v_pk_mul_f32 v[4:5], v[4:5], s[76:77] op_sel_hi:[1,0]
	v_pk_fma_f32 v[140:141], v[128:129], 0.5, v[134:135] op_sel_hi:[1,0,1]
	v_pk_fma_f32 v[138:139], v[126:127], 0.5, v[4:5] op_sel_hi:[1,0,1]
	v_sub_f32_e32 v5, v136, v201
	v_sub_f32_e32 v4, v175, v201
	v_sub_f32_e32 v135, v137, v201
	v_sub_f32_e32 v134, v203, v201
	v_pk_mul_f32 v[134:135], v[174:175], v[134:135] op_sel_hi:[0,1]
	v_pk_mul_f32 v[4:5], v[174:175], v[4:5] op_sel_hi:[0,1]
	s_waitcnt lgkmcnt(0)
	v_pk_fma_f32 v[4:5], v[142:143], v[4:5], v[146:147]
	v_pk_fma_f32 v[134:135], v[144:145], v[134:135], v[148:149]
	v_pk_mul_f32 v[4:5], v[4:5], s[76:77] op_sel_hi:[1,0]
	v_pk_mul_f32 v[134:135], v[134:135], s[76:77] op_sel_hi:[1,0]
	v_pk_fma_f32 v[216:217], v[130:131], 0.5, v[4:5] op_sel_hi:[1,0,1]
	v_pk_fma_f32 v[218:219], v[132:133], 0.5, v[134:135] op_sel_hi:[1,0,1]
	v_pk_add_f32 v[134:135], v[138:139], v[216:217]
	v_pk_add_f32 v[4:5], v[140:141], v[218:219]
	v_pk_mul_f32 v[136:137], v[216:217], v[216:217]
	v_pk_mul_f32 v[222:223], v[218:219], v[218:219]
	v_pk_fma_f32 v[136:137], v[138:139], v[138:139], v[136:137]
	v_pk_fma_f32 v[222:223], v[140:141], v[140:141], v[222:223]
	v_pk_mov_b32 v[224:225], v[134:135], v[4:5] op_sel:[1,0]
	v_mov_b32_e32 v135, v5
	v_pk_add_f32 v[4:5], v[224:225], v[134:135]
	v_pk_mov_b32 v[134:135], v[136:137], v[222:223] op_sel:[1,0]
	v_mov_b32_e32 v137, v223
	v_pk_add_f32 v[134:135], v[134:135], v[136:137]
	v_add_f32_e32 v2, v4, v5
	v_pk_add_f32 v[134:135], v[134:135], v[134:135] op_sel:[0,1] op_sel_hi:[1,0]
	v_cvt_pk_bf16_f32 v138, v138, v139
	v_cvt_pk_bf16_f32 v139, v140, v141
	v_cvt_pk_bf16_f32 v140, v216, v217
	v_lshl_add_u64 v[216:217], s[18:19], 0, v[206:207]
	v_add_f32_e32 v2, 0, v2
	v_mov_b32_e32 v4, v3
	v_mov_b32_e32 v5, v3
	v_mov_b32_e32 v135, v3
	v_mov_b32_e32 v136, v3
	v_mov_b32_e32 v137, v3
	v_cvt_pk_bf16_f32 v141, v218, v219
	v_lshl_add_u64 v[216:217], v[178:179], 1, v[216:217]
	global_store_dwordx4 v[216:217], v[138:141], off
	s_branch .LBB0_1049
